# init copy loop unrolled 16x; odd-layer weight transpose loops (in/ba/Z) issue all 4 tile loads before the first wait
# baseline (speedup 1.0000x reference)
; DEVI void tconv_seg(const float* src, int ld, int krows, int c0, int ncols, int ndst, bf16_t* dst, int dld,
;                     char* smem) {
;     ...
; #pragma unroll
;     for (int i = 0; i < 4; ++i) {
;       const int r = i * 16 + lr;
;       f32x4 v = f32x4{0.f, 0.f, 0.f, 0.f};
;       if (n0 + lc < ncols) v = *(const f32x4*)(src + (size_t)(k0 + r) * ld + c0 + n0 + lc);
;       tile[r * 65 + lc + 0] = v[0];
;       tile[r * 65 + lc + 1] = v[1];
;       tile[r * 65 + lc + 2] = v[2];
;       tile[r * 65 + lc + 3] = v[3];
;     }
.LBB0_1689:
	s_or_saveexec_b64 s[36:37], s[36:37]
	v_mov_b32_e32 v6, 0
	v_mov_b32_e32 v24, s18
	v_mov_b32_e32 v7, 0
	v_mov_b32_e32 v8, 0
	v_mov_b32_e32 v9, 0
	v_mov_b32_e32 v2, 0
	v_mov_b32_e32 v3, 0
	v_mov_b32_e32 v4, 0
	v_mov_b32_e32 v5, 0
	s_xor_b64 exec, exec, s[36:37]
	s_cbranch_execz .LBB0_1691
	s_lshl_b32 s13, s13, 10
	s_ashr_i32 s35, s34, 31
	s_sub_i32 s18, 0, s13
	s_sub_i32 s13, s5, s13
	v_lshl_add_u64 v[24:25], s[34:35], 2, v[10:11]
	v_add_u32_e32 v26, s13, v0
	s_movk_i32 s13, 0x4040
	v_mad_i64_i32 v[2:3], s[24:25], v26, s13, v[24:25]
	global_load_dwordx4 v[40:43], v[2:3], off
	v_add_u32_e32 v6, 16, v26
	v_mad_i64_i32 v[6:7], s[24:25], v6, s13, v[24:25]
	global_load_dwordx4 v[44:47], v[6:7], off
	v_add_u32_e32 v2, 32, v26
	v_add_u32_e32 v6, 48, v26
	v_mad_i64_i32 v[2:3], s[24:25], v2, s13, v[24:25]
	v_mad_i64_i32 v[6:7], s[24:25], v6, s13, v[24:25]
	global_load_dwordx4 v[2:5], v[2:3], off
	v_mov_b32_e32 v24, s18
	global_load_dwordx4 v[6:9], v[6:7], off
	s_waitcnt vmcnt(3)
	ds_write2_b32 v21, v40, v41 offset1:1
	ds_write2_b32 v21, v42, v43 offset0:2 offset1:3
	s_waitcnt vmcnt(2)
	ds_write2_b32 v22, v44, v45 offset1:1
	ds_write2_b32 v23, v46, v47 offset1:1

; DEVI void tconv_seg(const float* src, int ld, int krows, int c0, int ncols, int ndst, bf16_t* dst, int dld,
;                     char* smem) {
;     ...
; #pragma unroll
;     for (int i = 0; i < 4; ++i) {
;       const int r = i * 16 + lr;
;       f32x4 v = f32x4{0.f, 0.f, 0.f, 0.f};
;       if (n0 + lc < ncols) v = *(const f32x4*)(src + (size_t)(k0 + r) * ld + c0 + n0 + lc);
;       tile[r * 65 + lc + 0] = v[0];
;       tile[r * 65 + lc + 1] = v[1];
;       tile[r * 65 + lc + 2] = v[2];
;       tile[r * 65 + lc + 3] = v[3];
;     }
.LBB0_1735:
	s_or_saveexec_b64 s[34:35], s[34:35]
	v_mov_b32_e32 v6, 0
	v_mov_b32_e32 v24, s17
	v_mov_b32_e32 v7, 0
	v_mov_b32_e32 v8, 0
	v_mov_b32_e32 v9, 0
	v_mov_b32_e32 v2, 0
	v_mov_b32_e32 v3, 0
	v_mov_b32_e32 v4, 0
	v_mov_b32_e32 v5, 0
	s_xor_b64 exec, exec, s[34:35]
	s_cbranch_execz .LBB0_1737
	s_ashr_i32 s17, s16, 31
	s_lshl_b32 s13, s13, 10
	v_lshl_add_u64 v[24:25], s[16:17], 2, v[10:11]
	s_sub_i32 s17, 0, s13
	s_sub_i32 s13, s5, s13
	v_add_u32_e32 v26, s13, v0
	s_movk_i32 s13, 0x4040
	v_mad_i64_i32 v[2:3], s[24:25], v26, s13, v[24:25]
	global_load_dwordx4 v[40:43], v[2:3], off
	v_add_u32_e32 v6, 16, v26
	v_mad_i64_i32 v[6:7], s[24:25], v6, s13, v[24:25]
	global_load_dwordx4 v[44:47], v[6:7], off
	v_add_u32_e32 v2, 32, v26
	v_add_u32_e32 v6, 48, v26
	v_mad_i64_i32 v[2:3], s[24:25], v2, s13, v[24:25]
	v_mad_i64_i32 v[6:7], s[24:25], v6, s13, v[24:25]
	global_load_dwordx4 v[2:5], v[2:3], off
	v_mov_b32_e32 v24, s17
	global_load_dwordx4 v[6:9], v[6:7], off
	s_waitcnt vmcnt(3)
	ds_write2_b32 v21, v40, v41 offset1:1
	ds_write2_b32 v21, v42, v43 offset0:2 offset1:3
	s_waitcnt vmcnt(2)
	ds_write2_b32 v22, v44, v45 offset1:1
	ds_write2_b32 v23, v46, v47 offset1:1

; DEVI void init_phase(const Params& p) {
;     ...
;   for (int idx = gt; idx < L * 256; idx += nth) {
;     const int t = idx >> 8, c = (idx & 255) * 4;
;     f32x4 v = (t < 16) ? *(const f32x4*)(p.in[1] + t * 1024 + c) : *(const f32x4*)(p.in[0] + (size_t)(t - 16) * 1024 + c);
;     if (t < 16) *(f32x4*)(hfrow(p, t) + c) = v;
;     *(u32x2*)(hb + (size_t)t * 1024 + c) = u32x2{pack2(v[0], v[1]), pack2(v[2], v[3])};
;   }
.Lmy_init_main:
	s_or_b64 exec, exec, s[0:1]
	s_add_u32 s24, s14, 0x8000
	s_addc_u32 s25, s15, 0
	v_readfirstlane_b32 s0, v6
	s_lshl_b32 s1, s48, 8
	s_lshl_b32 s16, s48, 12
	s_lshl_b32 s17, s48, 11
	s_mul_i32 s5, s1, 15
	v_lshlrev_b32_e32 v12, 4, v6
	v_lshlrev_b32_e32 v13, 3, v6
.Lmy_init_loop:
	s_add_u32 s0, s0, s5
	s_cmp_lt_u32 s0, 0x400000
	s_cbranch_scc0 .Lmy_init_tailpre
	global_load_dwordx4 v[14:17], v12, s[68:69]
	v_add_u32_e32 v8, s16, v12
	global_load_dwordx4 v[18:21], v8, s[68:69]
	v_add_u32_e32 v8, s16, v8
	global_load_dwordx4 v[22:25], v8, s[68:69]
	v_add_u32_e32 v8, s16, v8
	global_load_dwordx4 v[26:29], v8, s[68:69]
	v_add_u32_e32 v8, s16, v8
	global_load_dwordx4 v[30:33], v8, s[68:69]
	v_add_u32_e32 v8, s16, v8
	global_load_dwordx4 v[34:37], v8, s[68:69]
	v_add_u32_e32 v8, s16, v8
	global_load_dwordx4 v[38:41], v8, s[68:69]
	v_add_u32_e32 v8, s16, v8
	global_load_dwordx4 v[42:45], v8, s[68:69]
	v_add_u32_e32 v8, s16, v8
	global_load_dwordx4 v[46:49], v8, s[68:69]
	v_add_u32_e32 v8, s16, v8
	global_load_dwordx4 v[50:53], v8, s[68:69]
	v_add_u32_e32 v8, s16, v8
	global_load_dwordx4 v[54:57], v8, s[68:69]
	v_add_u32_e32 v8, s16, v8
	global_load_dwordx4 v[58:61], v8, s[68:69]
	v_add_u32_e32 v8, s16, v8
	global_load_dwordx4 v[62:65], v8, s[68:69]
	v_add_u32_e32 v8, s16, v8
	global_load_dwordx4 v[66:69], v8, s[68:69]
	v_add_u32_e32 v8, s16, v8
	global_load_dwordx4 v[70:73], v8, s[68:69]
	v_add_u32_e32 v8, s16, v8
	global_load_dwordx4 v[74:77], v8, s[68:69]
	v_add_u32_e32 v12, s16, v8
	s_waitcnt vmcnt(15)
	v_cvt_pk_bf16_f32 v14, v14, v15
	v_cvt_pk_bf16_f32 v15, v16, v17
	s_waitcnt vmcnt(14)
	v_cvt_pk_bf16_f32 v18, v18, v19
	v_cvt_pk_bf16_f32 v19, v20, v21
	s_waitcnt vmcnt(13)
	v_cvt_pk_bf16_f32 v22, v22, v23
	v_cvt_pk_bf16_f32 v23, v24, v25
	s_waitcnt vmcnt(12)
	v_cvt_pk_bf16_f32 v26, v26, v27
	v_cvt_pk_bf16_f32 v27, v28, v29
	s_waitcnt vmcnt(11)
	v_cvt_pk_bf16_f32 v30, v30, v31
	v_cvt_pk_bf16_f32 v31, v32, v33
	s_waitcnt vmcnt(10)
	v_cvt_pk_bf16_f32 v34, v34, v35
	v_cvt_pk_bf16_f32 v35, v36, v37
	s_waitcnt vmcnt(9)
	v_cvt_pk_bf16_f32 v38, v38, v39
	v_cvt_pk_bf16_f32 v39, v40, v41
	s_waitcnt vmcnt(8)
	v_cvt_pk_bf16_f32 v42, v42, v43
	v_cvt_pk_bf16_f32 v43, v44, v45
	s_waitcnt vmcnt(7)
	v_cvt_pk_bf16_f32 v46, v46, v47
	v_cvt_pk_bf16_f32 v47, v48, v49
	s_waitcnt vmcnt(6)
	v_cvt_pk_bf16_f32 v50, v50, v51
	v_cvt_pk_bf16_f32 v51, v52, v53
	s_waitcnt vmcnt(5)
	v_cvt_pk_bf16_f32 v54, v54, v55
	v_cvt_pk_bf16_f32 v55, v56, v57
	s_waitcnt vmcnt(4)
	v_cvt_pk_bf16_f32 v58, v58, v59
	v_cvt_pk_bf16_f32 v59, v60, v61
	s_waitcnt vmcnt(3)
	v_cvt_pk_bf16_f32 v62, v62, v63
	v_cvt_pk_bf16_f32 v63, v64, v65
	s_waitcnt vmcnt(2)
	v_cvt_pk_bf16_f32 v66, v66, v67
	v_cvt_pk_bf16_f32 v67, v68, v69
	s_waitcnt vmcnt(1)
	v_cvt_pk_bf16_f32 v70, v70, v71
	v_cvt_pk_bf16_f32 v71, v72, v73
	s_waitcnt vmcnt(0)
	v_cvt_pk_bf16_f32 v74, v74, v75
	v_cvt_pk_bf16_f32 v75, v76, v77
	global_store_dwordx2 v13, v[14:15], s[24:25]
	v_add_u32_e32 v13, s17, v13
	global_store_dwordx2 v13, v[18:19], s[24:25]
	v_add_u32_e32 v13, s17, v13
	global_store_dwordx2 v13, v[22:23], s[24:25]
	v_add_u32_e32 v13, s17, v13
	global_store_dwordx2 v13, v[26:27], s[24:25]
	v_add_u32_e32 v13, s17, v13
	global_store_dwordx2 v13, v[30:31], s[24:25]
	v_add_u32_e32 v13, s17, v13
	global_store_dwordx2 v13, v[34:35], s[24:25]
	v_add_u32_e32 v13, s17, v13
	global_store_dwordx2 v13, v[38:39], s[24:25]
	v_add_u32_e32 v13, s17, v13
	global_store_dwordx2 v13, v[42:43], s[24:25]
	v_add_u32_e32 v13, s17, v13
	global_store_dwordx2 v13, v[46:47], s[24:25]
	v_add_u32_e32 v13, s17, v13
	global_store_dwordx2 v13, v[50:51], s[24:25]
	v_add_u32_e32 v13, s17, v13
	global_store_dwordx2 v13, v[54:55], s[24:25]
	v_add_u32_e32 v13, s17, v13
	global_store_dwordx2 v13, v[58:59], s[24:25]
	v_add_u32_e32 v13, s17, v13
	global_store_dwordx2 v13, v[62:63], s[24:25]
	v_add_u32_e32 v13, s17, v13
	global_store_dwordx2 v13, v[66:67], s[24:25]
	v_add_u32_e32 v13, s17, v13
	global_store_dwordx2 v13, v[70:71], s[24:25]
	v_add_u32_e32 v13, s17, v13
	global_store_dwordx2 v13, v[74:75], s[24:25]
	v_add_u32_e32 v13, s17, v13
	s_add_u32 s0, s0, s1
	s_branch .Lmy_init_loop
